# fused final-norm epilogue: first two residual rows fetched during the last K trip of the down GEMM; gain fetched behind the exchange
# speedup vs baseline: 1.0035x; 1.0035x over previous
.LBB0_790:
	ds_read_b128 v[144:147], v184
	ds_read_b128 v[148:151], v184 offset:1024
	ds_read_b128 v[152:155], v184 offset:2048
	ds_read_b128 v[156:159], v184 offset:3072
	ds_read_b128 v[160:163], v185
	ds_read_b128 v[164:167], v185 offset:1024
	ds_read_b128 v[168:171], v185 offset:2048
	ds_read_b128 v[172:175], v185 offset:3072
	s_add_u32 s37, s38, 0x4000
	s_addc_u32 s40, s39, 0
	s_cmp_eq_u32 s33, 60
	s_cselect_b32 s44, s30, s37
	s_cselect_b32 s45, s31, s40
	s_cselect_b32 s42, s34, s11
	s_cselect_b32 s43, s35, s29
	s_add_u32 s40, s44, 0x8000
	s_addc_u32 s41, s45, 0
	v_lshl_add_u64 v[176:177], s[38:39], 0, v[136:137]
	s_add_i32 m0, s50, 0xc000
	ds_read_b128 v[192:195], v186
	ds_read_b128 v[196:199], v186 offset:1024
	ds_read_b128 v[202:205], v186 offset:2048
	ds_read_b128 v[206:209], v186 offset:3072
	ds_read_b128 v[210:213], v186 offset:4096
	ds_read_b128 v[214:217], v186 offset:5120
	ds_read_b128 v[218:221], v186 offset:6144
	ds_read_b128 v[222:225], v186 offset:7168
	global_load_lds_dwordx4 v[176:177], off
	v_lshl_add_u64 v[176:177], s[38:39], 0, v[138:139]
	s_add_i32 m0, s50, 0xe000
	s_nop 0
	global_load_lds_dwordx4 v[176:177], off
	s_waitcnt vmcnt(8)
	s_waitcnt lgkmcnt(0)
	s_barrier
	s_setprio 1
	s_waitcnt lgkmcnt(0)
	v_mfma_f32_16x16x32_bf16 v[124:127], v[144:147], v[192:195], v[124:127]
	v_mfma_f32_16x16x32_bf16 v[120:123], v[152:155], v[192:195], v[120:123]
	v_mfma_f32_16x16x32_bf16 v[108:111], v[144:147], v[202:205], v[108:111]
	v_mfma_f32_16x16x32_bf16 v[104:107], v[152:155], v[202:205], v[104:107]
	v_mfma_f32_16x16x32_bf16 v[92:95], v[144:147], v[210:213], v[92:95]
	v_mfma_f32_16x16x32_bf16 v[88:91], v[152:155], v[210:213], v[88:91]
	v_mfma_f32_16x16x32_bf16 v[76:79], v[144:147], v[218:221], v[76:79]
	v_mfma_f32_16x16x32_bf16 v[72:75], v[152:155], v[218:221], v[72:75]
	v_mfma_f32_16x16x32_bf16 v[124:127], v[148:151], v[196:199], v[124:127]
	v_mfma_f32_16x16x32_bf16 v[120:123], v[156:159], v[196:199], v[120:123]
	v_mfma_f32_16x16x32_bf16 v[108:111], v[148:151], v[206:209], v[108:111]
	v_mfma_f32_16x16x32_bf16 v[104:107], v[156:159], v[206:209], v[104:107]
	v_mfma_f32_16x16x32_bf16 v[92:95], v[148:151], v[214:217], v[92:95]
	v_mfma_f32_16x16x32_bf16 v[88:91], v[156:159], v[214:217], v[88:91]
	v_mfma_f32_16x16x32_bf16 v[76:79], v[148:151], v[222:225], v[76:79]
	v_mfma_f32_16x16x32_bf16 v[72:75], v[156:159], v[222:225], v[72:75]
	s_setprio 0
	s_setprio 1
	v_mfma_f32_16x16x32_bf16 v[116:119], v[160:163], v[192:195], v[116:119]
	v_mfma_f32_16x16x32_bf16 v[112:115], v[168:171], v[192:195], v[112:115]
	v_mfma_f32_16x16x32_bf16 v[100:103], v[160:163], v[202:205], v[100:103]
	v_mfma_f32_16x16x32_bf16 v[96:99], v[168:171], v[202:205], v[96:99]
	v_mfma_f32_16x16x32_bf16 v[84:87], v[160:163], v[210:213], v[84:87]
	v_mfma_f32_16x16x32_bf16 v[80:83], v[168:171], v[210:213], v[80:83]
	v_mfma_f32_16x16x32_bf16 v[68:71], v[160:163], v[218:221], v[68:71]
	v_mfma_f32_16x16x32_bf16 v[64:67], v[168:171], v[218:221], v[64:67]
	v_mfma_f32_16x16x32_bf16 v[116:119], v[164:167], v[196:199], v[116:119]
	v_mfma_f32_16x16x32_bf16 v[112:115], v[172:175], v[196:199], v[112:115]
	v_mfma_f32_16x16x32_bf16 v[100:103], v[164:167], v[206:209], v[100:103]
	v_mfma_f32_16x16x32_bf16 v[96:99], v[172:175], v[206:209], v[96:99]
	v_mfma_f32_16x16x32_bf16 v[84:87], v[164:167], v[214:217], v[84:87]
	v_mfma_f32_16x16x32_bf16 v[80:83], v[172:175], v[214:217], v[80:83]
	v_mfma_f32_16x16x32_bf16 v[68:71], v[164:167], v[222:225], v[68:71]
	v_mfma_f32_16x16x32_bf16 v[64:67], v[172:175], v[222:225], v[64:67]
	s_setprio 0
	s_barrier
	s_add_i32 s37, s59, s49
	v_lshl_add_u64 v[176:177], s[42:43], 0, v[130:131]
	s_mov_b32 m0, s37
	ds_read_b128 v[192:195], v186 offset:16384
	ds_read_b128 v[196:199], v186 offset:17408
	ds_read_b128 v[202:205], v186 offset:18432
	ds_read_b128 v[206:209], v186 offset:19456
	ds_read_b128 v[210:213], v186 offset:20480
	ds_read_b128 v[214:217], v186 offset:21504
	ds_read_b128 v[218:221], v186 offset:22528
	ds_read_b128 v[222:225], v186 offset:23552
	global_load_lds_dwordx4 v[176:177], off
	s_add_i32 m0, s37, 0x2000
	s_add_u32 s64, s42, 0x100000
	v_lshl_add_u64 v[226:227], s[42:43], 0, v[134:135]
	s_addc_u32 s65, s43, 0
	s_add_i32 s37, s60, s49
	global_load_lds_dwordx4 v[226:227], off
	v_lshl_add_u64 v[228:229], s[64:65], 0, v[130:131]
	s_mov_b32 m0, s37
	s_nop 0
	global_load_lds_dwordx4 v[228:229], off
	v_lshl_add_u64 v[228:229], s[64:65], 0, v[134:135]
	s_add_i32 m0, s37, 0x2000
	s_nop 0
	global_load_lds_dwordx4 v[228:229], off
	v_lshl_add_u64 v[228:229], s[44:45], 0, v[128:129]
	s_mov_b32 m0, s50
	s_nop 0
	global_load_lds_dwordx4 v[228:229], off
	v_lshl_add_u64 v[228:229], s[44:45], 0, v[132:133]
	s_mov_b32 m0, s51
	s_nop 0
	global_load_lds_dwordx4 v[228:229], off
	s_waitcnt vmcnt(8)
	s_waitcnt lgkmcnt(0)
	s_barrier
	s_setprio 1
	s_waitcnt lgkmcnt(0)
	v_mfma_f32_16x16x32_bf16 v[60:63], v[144:147], v[192:195], v[60:63]
	v_mfma_f32_16x16x32_bf16 v[56:59], v[152:155], v[192:195], v[56:59]
	v_mfma_f32_16x16x32_bf16 v[44:47], v[144:147], v[202:205], v[44:47]
	v_mfma_f32_16x16x32_bf16 v[40:43], v[152:155], v[202:205], v[40:43]
	v_mfma_f32_16x16x32_bf16 v[28:31], v[144:147], v[210:213], v[28:31]
	v_mfma_f32_16x16x32_bf16 v[24:27], v[152:155], v[210:213], v[24:27]
	v_mfma_f32_16x16x32_bf16 v[12:15], v[144:147], v[218:221], v[12:15]
	v_mfma_f32_16x16x32_bf16 v[8:11], v[152:155], v[218:221], v[8:11]
	v_mfma_f32_16x16x32_bf16 v[60:63], v[148:151], v[196:199], v[60:63]
	v_mfma_f32_16x16x32_bf16 v[56:59], v[156:159], v[196:199], v[56:59]
	v_mfma_f32_16x16x32_bf16 v[44:47], v[148:151], v[206:209], v[44:47]
	v_mfma_f32_16x16x32_bf16 v[40:43], v[156:159], v[206:209], v[40:43]
	v_mfma_f32_16x16x32_bf16 v[28:31], v[148:151], v[214:217], v[28:31]
	v_mfma_f32_16x16x32_bf16 v[24:27], v[156:159], v[214:217], v[24:27]
	v_mfma_f32_16x16x32_bf16 v[12:15], v[148:151], v[222:225], v[12:15]
	v_mfma_f32_16x16x32_bf16 v[8:11], v[156:159], v[222:225], v[8:11]
	s_setprio 0
	s_setprio 1
	v_mfma_f32_16x16x32_bf16 v[52:55], v[160:163], v[192:195], v[52:55]
	v_mfma_f32_16x16x32_bf16 v[48:51], v[168:171], v[192:195], v[48:51]
	v_mfma_f32_16x16x32_bf16 v[36:39], v[160:163], v[202:205], v[36:39]
	v_mfma_f32_16x16x32_bf16 v[32:35], v[168:171], v[202:205], v[32:35]
	v_mfma_f32_16x16x32_bf16 v[20:23], v[160:163], v[210:213], v[20:23]
	v_mfma_f32_16x16x32_bf16 v[16:19], v[168:171], v[210:213], v[16:19]
	v_mfma_f32_16x16x32_bf16 v[4:7], v[160:163], v[218:221], v[4:7]
	v_mfma_f32_16x16x32_bf16 v[0:3], v[168:171], v[218:221], v[0:3]
	v_mfma_f32_16x16x32_bf16 v[52:55], v[164:167], v[196:199], v[52:55]
	v_mfma_f32_16x16x32_bf16 v[48:51], v[172:175], v[196:199], v[48:51]
	v_mfma_f32_16x16x32_bf16 v[36:39], v[164:167], v[206:209], v[36:39]
	v_mfma_f32_16x16x32_bf16 v[32:35], v[172:175], v[206:209], v[32:35]
	v_mfma_f32_16x16x32_bf16 v[20:23], v[164:167], v[214:217], v[20:23]
	v_mfma_f32_16x16x32_bf16 v[16:19], v[172:175], v[214:217], v[16:19]
	v_mfma_f32_16x16x32_bf16 v[4:7], v[164:167], v[222:225], v[4:7]
	v_mfma_f32_16x16x32_bf16 v[0:3], v[172:175], v[222:225], v[0:3]
	s_setprio 0
	s_barrier
	s_add_i32 s37, 0, 0x18000
	s_add_i32 s63, 0, 0x1c000
	v_add_u32_e32 v156, s37, v179
	v_add_u32_e32 v172, s63, v179
	ds_read_b128 v[144:147], v156
	ds_read_b128 v[148:151], v156 offset:1024
	ds_read_b128 v[152:155], v156 offset:2048
	ds_read_b128 v[156:159], v156 offset:3072
	ds_read_b128 v[160:163], v172
	ds_read_b128 v[164:167], v172 offset:1024
	ds_read_b128 v[168:171], v172 offset:2048
	ds_read_b128 v[172:175], v172 offset:3072
	s_add_u32 s44, s44, 0x4000
	s_addc_u32 s45, s45, 0
	s_mov_b32 m0, s52
	v_lshl_add_u64 v[228:229], s[44:45], 0, v[128:129]
	ds_read_b128 v[192:195], v186 offset:32768
	ds_read_b128 v[196:199], v186 offset:33792
	ds_read_b128 v[202:205], v186 offset:34816
	ds_read_b128 v[206:209], v186 offset:35840
	ds_read_b128 v[210:213], v186 offset:36864
	ds_read_b128 v[214:217], v186 offset:37888
	ds_read_b128 v[218:221], v186 offset:38912
	ds_read_b128 v[222:225], v186 offset:39936
	global_load_lds_dwordx4 v[228:229], off
	v_lshl_add_u64 v[228:229], s[44:45], 0, v[132:133]
	s_mov_b32 m0, s53
	s_nop 0
	global_load_lds_dwordx4 v[228:229], off
	s_waitcnt vmcnt(8)
	s_waitcnt lgkmcnt(0)
	s_barrier
	s_setprio 1
	s_waitcnt lgkmcnt(0)
	v_mfma_f32_16x16x32_bf16 v[124:127], v[144:147], v[192:195], v[124:127]
	v_mfma_f32_16x16x32_bf16 v[120:123], v[152:155], v[192:195], v[120:123]
	v_mfma_f32_16x16x32_bf16 v[108:111], v[144:147], v[202:205], v[108:111]
	v_mfma_f32_16x16x32_bf16 v[104:107], v[152:155], v[202:205], v[104:107]
	v_mfma_f32_16x16x32_bf16 v[92:95], v[144:147], v[210:213], v[92:95]
	v_mfma_f32_16x16x32_bf16 v[88:91], v[152:155], v[210:213], v[88:91]
	v_mfma_f32_16x16x32_bf16 v[76:79], v[144:147], v[218:221], v[76:79]
	v_mfma_f32_16x16x32_bf16 v[72:75], v[152:155], v[218:221], v[72:75]
	v_mfma_f32_16x16x32_bf16 v[124:127], v[148:151], v[196:199], v[124:127]
	v_mfma_f32_16x16x32_bf16 v[120:123], v[156:159], v[196:199], v[120:123]
	v_mfma_f32_16x16x32_bf16 v[108:111], v[148:151], v[206:209], v[108:111]
	v_mfma_f32_16x16x32_bf16 v[104:107], v[156:159], v[206:209], v[104:107]
	v_mfma_f32_16x16x32_bf16 v[92:95], v[148:151], v[214:217], v[92:95]
	v_mfma_f32_16x16x32_bf16 v[88:91], v[156:159], v[214:217], v[88:91]
	v_mfma_f32_16x16x32_bf16 v[76:79], v[148:151], v[222:225], v[76:79]
	v_mfma_f32_16x16x32_bf16 v[72:75], v[156:159], v[222:225], v[72:75]
	s_setprio 0
	s_setprio 1
	v_mfma_f32_16x16x32_bf16 v[116:119], v[160:163], v[192:195], v[116:119]
	v_mfma_f32_16x16x32_bf16 v[112:115], v[168:171], v[192:195], v[112:115]
	v_mfma_f32_16x16x32_bf16 v[100:103], v[160:163], v[202:205], v[100:103]
	v_mfma_f32_16x16x32_bf16 v[96:99], v[168:171], v[202:205], v[96:99]
	v_mfma_f32_16x16x32_bf16 v[84:87], v[160:163], v[210:213], v[84:87]
	v_mfma_f32_16x16x32_bf16 v[80:83], v[168:171], v[210:213], v[80:83]
	v_mfma_f32_16x16x32_bf16 v[68:71], v[160:163], v[218:221], v[68:71]
	v_mfma_f32_16x16x32_bf16 v[64:67], v[168:171], v[218:221], v[64:67]
	v_mfma_f32_16x16x32_bf16 v[116:119], v[164:167], v[196:199], v[116:119]
	v_mfma_f32_16x16x32_bf16 v[112:115], v[172:175], v[196:199], v[112:115]
	v_mfma_f32_16x16x32_bf16 v[100:103], v[164:167], v[206:209], v[100:103]
	v_mfma_f32_16x16x32_bf16 v[96:99], v[172:175], v[206:209], v[96:99]
	v_mfma_f32_16x16x32_bf16 v[84:87], v[164:167], v[214:217], v[84:87]
	v_mfma_f32_16x16x32_bf16 v[80:83], v[172:175], v[214:217], v[80:83]
	v_mfma_f32_16x16x32_bf16 v[68:71], v[164:167], v[222:225], v[68:71]
	v_mfma_f32_16x16x32_bf16 v[64:67], v[172:175], v[222:225], v[64:67]
	s_setprio 0
	s_barrier
	s_add_i32 s37, s37, s49
	v_lshl_add_u64 v[176:177], v[176:177], 0, s[18:19]
	s_mov_b32 m0, s37
	ds_read_b128 v[192:195], v186 offset:49152
	ds_read_b128 v[196:199], v186 offset:50176
	ds_read_b128 v[202:205], v186 offset:51200
	ds_read_b128 v[206:209], v186 offset:52224
	ds_read_b128 v[210:213], v186 offset:53248
	ds_read_b128 v[214:217], v186 offset:54272
	ds_read_b128 v[218:221], v186 offset:55296
	ds_read_b128 v[222:225], v186 offset:56320
	global_load_lds_dwordx4 v[176:177], off
	s_add_i32 m0, s37, 0x2000
	s_add_u32 s42, s42, 0x100080
	v_lshl_add_u64 v[176:177], v[226:227], 0, s[18:19]
	s_addc_u32 s43, s43, 0
	s_add_i32 s37, s63, s49
	global_load_lds_dwordx4 v[176:177], off
	v_lshl_add_u64 v[176:177], s[42:43], 0, v[130:131]
	s_mov_b32 m0, s37
	s_nop 0
	global_load_lds_dwordx4 v[176:177], off
	v_lshl_add_u64 v[176:177], s[42:43], 0, v[134:135]
	s_add_i32 m0, s37, 0x2000
	s_nop 0
	global_load_lds_dwordx4 v[176:177], off
	v_lshl_add_u64 v[176:177], s[40:41], 0, v[128:129]
	s_mov_b32 m0, s57
	s_nop 0
	global_load_lds_dwordx4 v[176:177], off
	v_lshl_add_u64 v[176:177], s[40:41], 0, v[132:133]
	s_mov_b32 m0, s58
	s_nop 0
	global_load_lds_dwordx4 v[176:177], off
	s_waitcnt vmcnt(8)
	s_waitcnt lgkmcnt(0)
	s_barrier
	s_setprio 1
	s_waitcnt lgkmcnt(0)
	v_mfma_f32_16x16x32_bf16 v[60:63], v[144:147], v[192:195], v[60:63]
	v_mfma_f32_16x16x32_bf16 v[56:59], v[152:155], v[192:195], v[56:59]
	v_mfma_f32_16x16x32_bf16 v[44:47], v[144:147], v[202:205], v[44:47]
	v_mfma_f32_16x16x32_bf16 v[40:43], v[152:155], v[202:205], v[40:43]
	v_mfma_f32_16x16x32_bf16 v[28:31], v[144:147], v[210:213], v[28:31]
	v_mfma_f32_16x16x32_bf16 v[24:27], v[152:155], v[210:213], v[24:27]
	v_mfma_f32_16x16x32_bf16 v[12:15], v[144:147], v[218:221], v[12:15]
	v_mfma_f32_16x16x32_bf16 v[8:11], v[152:155], v[218:221], v[8:11]
	v_mfma_f32_16x16x32_bf16 v[60:63], v[148:151], v[196:199], v[60:63]
	v_mfma_f32_16x16x32_bf16 v[56:59], v[156:159], v[196:199], v[56:59]
	v_mfma_f32_16x16x32_bf16 v[44:47], v[148:151], v[206:209], v[44:47]
	v_mfma_f32_16x16x32_bf16 v[40:43], v[156:159], v[206:209], v[40:43]
	v_mfma_f32_16x16x32_bf16 v[28:31], v[148:151], v[214:217], v[28:31]
	v_mfma_f32_16x16x32_bf16 v[24:27], v[156:159], v[214:217], v[24:27]
	v_mfma_f32_16x16x32_bf16 v[12:15], v[148:151], v[222:225], v[12:15]
	v_mfma_f32_16x16x32_bf16 v[8:11], v[156:159], v[222:225], v[8:11]
	s_setprio 0
	s_setprio 1
	v_mfma_f32_16x16x32_bf16 v[52:55], v[160:163], v[192:195], v[52:55]
	v_mfma_f32_16x16x32_bf16 v[48:51], v[168:171], v[192:195], v[48:51]
	v_mfma_f32_16x16x32_bf16 v[36:39], v[160:163], v[202:205], v[36:39]
	v_mfma_f32_16x16x32_bf16 v[32:35], v[168:171], v[202:205], v[32:35]
	v_mfma_f32_16x16x32_bf16 v[20:23], v[160:163], v[210:213], v[20:23]
	v_mfma_f32_16x16x32_bf16 v[16:19], v[168:171], v[210:213], v[16:19]
	v_mfma_f32_16x16x32_bf16 v[4:7], v[160:163], v[218:221], v[4:7]
	v_mfma_f32_16x16x32_bf16 v[0:3], v[168:171], v[218:221], v[0:3]
	v_mfma_f32_16x16x32_bf16 v[52:55], v[164:167], v[196:199], v[52:55]
	v_mfma_f32_16x16x32_bf16 v[48:51], v[172:175], v[196:199], v[48:51]
	v_mfma_f32_16x16x32_bf16 v[36:39], v[164:167], v[206:209], v[36:39]
	v_mfma_f32_16x16x32_bf16 v[32:35], v[172:175], v[206:209], v[32:35]
	v_mfma_f32_16x16x32_bf16 v[20:23], v[164:167], v[214:217], v[20:23]
	v_mfma_f32_16x16x32_bf16 v[16:19], v[172:175], v[214:217], v[16:19]
	v_mfma_f32_16x16x32_bf16 v[4:7], v[164:167], v[222:225], v[4:7]
	v_mfma_f32_16x16x32_bf16 v[0:3], v[172:175], v[222:225], v[0:3]
	s_setprio 0
	s_barrier
	s_add_i32 s33, s33, 2
	s_add_u32 s11, s11, 0x100
	s_addc_u32 s29, s29, 0
	s_add_u32 s38, s38, 0x10000
	s_addc_u32 s39, s39, 0
	s_cmp_gt_u32 s33, 59
	s_cbranch_scc0 .LBB0_790
	v_lshl_add_u32 v246, s10, 8, v178
	v_lshl_or_b32 v247, s36, 8, v180
	v_lshlrev_b32_e32 v246, 11, v246
	v_lshl_add_u32 v246, v247, 1, v246
	v_add_u32_e32 v247, 0x8000, v246
	global_load_dwordx4 v[230:233], v246, s[24:25]
	global_load_dwordx4 v[234:237], v246, s[24:25] offset:256
	global_load_dwordx4 v[238:241], v247, s[24:25]
	global_load_dwordx4 v[242:245], v247, s[24:25] offset:256
	ds_read_b128 v[144:147], v184
	ds_read_b128 v[148:151], v184 offset:1024
	ds_read_b128 v[152:155], v184 offset:2048
	ds_read_b128 v[156:159], v184 offset:3072
	ds_read_b128 v[160:163], v185
	ds_read_b128 v[164:167], v185 offset:1024
	ds_read_b128 v[168:171], v185 offset:2048
	ds_read_b128 v[172:175], v185 offset:3072
	s_add_u32 s37, s38, 0x4000
	s_addc_u32 s40, s39, 0
	s_cmp_eq_u32 s33, 60
	s_cselect_b32 s44, s30, s37
	s_cselect_b32 s45, s31, s40
	s_cselect_b32 s42, s34, s11
	s_cselect_b32 s43, s35, s29
	s_add_u32 s40, s44, 0x8000
	s_addc_u32 s41, s45, 0
	v_lshl_add_u64 v[176:177], s[38:39], 0, v[136:137]
	s_add_i32 m0, s50, 0xc000
	ds_read_b128 v[192:195], v186
	ds_read_b128 v[196:199], v186 offset:1024
	ds_read_b128 v[202:205], v186 offset:2048
	ds_read_b128 v[206:209], v186 offset:3072
	ds_read_b128 v[210:213], v186 offset:4096
	ds_read_b128 v[214:217], v186 offset:5120
	ds_read_b128 v[218:221], v186 offset:6144
	ds_read_b128 v[222:225], v186 offset:7168
	global_load_lds_dwordx4 v[176:177], off
	v_lshl_add_u64 v[176:177], s[38:39], 0, v[138:139]
	s_add_i32 m0, s50, 0xe000
	s_nop 0
	global_load_lds_dwordx4 v[176:177], off
	s_waitcnt vmcnt(12)
	s_waitcnt lgkmcnt(0)
	s_barrier
	s_setprio 1
	s_waitcnt lgkmcnt(0)
	v_mfma_f32_16x16x32_bf16 v[124:127], v[144:147], v[192:195], v[124:127]
	v_mfma_f32_16x16x32_bf16 v[120:123], v[152:155], v[192:195], v[120:123]
	v_mfma_f32_16x16x32_bf16 v[108:111], v[144:147], v[202:205], v[108:111]
	v_mfma_f32_16x16x32_bf16 v[104:107], v[152:155], v[202:205], v[104:107]
	v_mfma_f32_16x16x32_bf16 v[92:95], v[144:147], v[210:213], v[92:95]
	v_mfma_f32_16x16x32_bf16 v[88:91], v[152:155], v[210:213], v[88:91]
	v_mfma_f32_16x16x32_bf16 v[76:79], v[144:147], v[218:221], v[76:79]
	v_mfma_f32_16x16x32_bf16 v[72:75], v[152:155], v[218:221], v[72:75]
	v_mfma_f32_16x16x32_bf16 v[124:127], v[148:151], v[196:199], v[124:127]
	v_mfma_f32_16x16x32_bf16 v[120:123], v[156:159], v[196:199], v[120:123]
	v_mfma_f32_16x16x32_bf16 v[108:111], v[148:151], v[206:209], v[108:111]
	v_mfma_f32_16x16x32_bf16 v[104:107], v[156:159], v[206:209], v[104:107]
	v_mfma_f32_16x16x32_bf16 v[92:95], v[148:151], v[214:217], v[92:95]
	v_mfma_f32_16x16x32_bf16 v[88:91], v[156:159], v[214:217], v[88:91]
	v_mfma_f32_16x16x32_bf16 v[76:79], v[148:151], v[222:225], v[76:79]
	v_mfma_f32_16x16x32_bf16 v[72:75], v[156:159], v[222:225], v[72:75]
	s_setprio 0
	s_setprio 1
	v_mfma_f32_16x16x32_bf16 v[116:119], v[160:163], v[192:195], v[116:119]
	v_mfma_f32_16x16x32_bf16 v[112:115], v[168:171], v[192:195], v[112:115]
	v_mfma_f32_16x16x32_bf16 v[100:103], v[160:163], v[202:205], v[100:103]
	v_mfma_f32_16x16x32_bf16 v[96:99], v[168:171], v[202:205], v[96:99]
	v_mfma_f32_16x16x32_bf16 v[84:87], v[160:163], v[210:213], v[84:87]
	v_mfma_f32_16x16x32_bf16 v[80:83], v[168:171], v[210:213], v[80:83]
	v_mfma_f32_16x16x32_bf16 v[68:71], v[160:163], v[218:221], v[68:71]
	v_mfma_f32_16x16x32_bf16 v[64:67], v[168:171], v[218:221], v[64:67]
	v_mfma_f32_16x16x32_bf16 v[116:119], v[164:167], v[196:199], v[116:119]
	v_mfma_f32_16x16x32_bf16 v[112:115], v[172:175], v[196:199], v[112:115]
	v_mfma_f32_16x16x32_bf16 v[100:103], v[164:167], v[206:209], v[100:103]
	v_mfma_f32_16x16x32_bf16 v[96:99], v[172:175], v[206:209], v[96:99]
	v_mfma_f32_16x16x32_bf16 v[84:87], v[164:167], v[214:217], v[84:87]
	v_mfma_f32_16x16x32_bf16 v[80:83], v[172:175], v[214:217], v[80:83]
	v_mfma_f32_16x16x32_bf16 v[68:71], v[164:167], v[222:225], v[68:71]
	v_mfma_f32_16x16x32_bf16 v[64:67], v[172:175], v[222:225], v[64:67]
	s_setprio 0
	s_barrier
	s_add_i32 s37, s59, s49
	v_lshl_add_u64 v[176:177], s[42:43], 0, v[130:131]
	s_mov_b32 m0, s37
	ds_read_b128 v[192:195], v186 offset:16384
	ds_read_b128 v[196:199], v186 offset:17408
	ds_read_b128 v[202:205], v186 offset:18432
	ds_read_b128 v[206:209], v186 offset:19456
	ds_read_b128 v[210:213], v186 offset:20480
	ds_read_b128 v[214:217], v186 offset:21504
	ds_read_b128 v[218:221], v186 offset:22528
	ds_read_b128 v[222:225], v186 offset:23552
	global_load_lds_dwordx4 v[176:177], off
	s_add_i32 m0, s37, 0x2000
	s_add_u32 s64, s42, 0x100000
	v_lshl_add_u64 v[226:227], s[42:43], 0, v[134:135]
	s_addc_u32 s65, s43, 0
	s_add_i32 s37, s60, s49
	global_load_lds_dwordx4 v[226:227], off
	v_lshl_add_u64 v[228:229], s[64:65], 0, v[130:131]
	s_mov_b32 m0, s37
	s_nop 0
	global_load_lds_dwordx4 v[228:229], off
	v_lshl_add_u64 v[228:229], s[64:65], 0, v[134:135]
	s_add_i32 m0, s37, 0x2000
	s_nop 0
	global_load_lds_dwordx4 v[228:229], off
	v_lshl_add_u64 v[228:229], s[44:45], 0, v[128:129]
	s_mov_b32 m0, s50
	s_nop 0
	global_load_lds_dwordx4 v[228:229], off
	v_lshl_add_u64 v[228:229], s[44:45], 0, v[132:133]
	s_mov_b32 m0, s51
	s_nop 0
	global_load_lds_dwordx4 v[228:229], off
	s_waitcnt vmcnt(12)
	s_waitcnt lgkmcnt(0)
	s_barrier
	s_setprio 1
	s_waitcnt lgkmcnt(0)
	v_mfma_f32_16x16x32_bf16 v[60:63], v[144:147], v[192:195], v[60:63]
	v_mfma_f32_16x16x32_bf16 v[56:59], v[152:155], v[192:195], v[56:59]
	v_mfma_f32_16x16x32_bf16 v[44:47], v[144:147], v[202:205], v[44:47]
	v_mfma_f32_16x16x32_bf16 v[40:43], v[152:155], v[202:205], v[40:43]
	v_mfma_f32_16x16x32_bf16 v[28:31], v[144:147], v[210:213], v[28:31]
	v_mfma_f32_16x16x32_bf16 v[24:27], v[152:155], v[210:213], v[24:27]
	v_mfma_f32_16x16x32_bf16 v[12:15], v[144:147], v[218:221], v[12:15]
	v_mfma_f32_16x16x32_bf16 v[8:11], v[152:155], v[218:221], v[8:11]
	v_mfma_f32_16x16x32_bf16 v[60:63], v[148:151], v[196:199], v[60:63]
	v_mfma_f32_16x16x32_bf16 v[56:59], v[156:159], v[196:199], v[56:59]
	v_mfma_f32_16x16x32_bf16 v[44:47], v[148:151], v[206:209], v[44:47]
	v_mfma_f32_16x16x32_bf16 v[40:43], v[156:159], v[206:209], v[40:43]
	v_mfma_f32_16x16x32_bf16 v[28:31], v[148:151], v[214:217], v[28:31]
	v_mfma_f32_16x16x32_bf16 v[24:27], v[156:159], v[214:217], v[24:27]
	v_mfma_f32_16x16x32_bf16 v[12:15], v[148:151], v[222:225], v[12:15]
	v_mfma_f32_16x16x32_bf16 v[8:11], v[156:159], v[222:225], v[8:11]
	s_setprio 0
	s_setprio 1
	v_mfma_f32_16x16x32_bf16 v[52:55], v[160:163], v[192:195], v[52:55]
	v_mfma_f32_16x16x32_bf16 v[48:51], v[168:171], v[192:195], v[48:51]
	v_mfma_f32_16x16x32_bf16 v[36:39], v[160:163], v[202:205], v[36:39]
	v_mfma_f32_16x16x32_bf16 v[32:35], v[168:171], v[202:205], v[32:35]
	v_mfma_f32_16x16x32_bf16 v[20:23], v[160:163], v[210:213], v[20:23]
	v_mfma_f32_16x16x32_bf16 v[16:19], v[168:171], v[210:213], v[16:19]
	v_mfma_f32_16x16x32_bf16 v[4:7], v[160:163], v[218:221], v[4:7]
	v_mfma_f32_16x16x32_bf16 v[0:3], v[168:171], v[218:221], v[0:3]
	v_mfma_f32_16x16x32_bf16 v[52:55], v[164:167], v[196:199], v[52:55]
	v_mfma_f32_16x16x32_bf16 v[48:51], v[172:175], v[196:199], v[48:51]
	v_mfma_f32_16x16x32_bf16 v[36:39], v[164:167], v[206:209], v[36:39]
	v_mfma_f32_16x16x32_bf16 v[32:35], v[172:175], v[206:209], v[32:35]
	v_mfma_f32_16x16x32_bf16 v[20:23], v[164:167], v[214:217], v[20:23]
	v_mfma_f32_16x16x32_bf16 v[16:19], v[172:175], v[214:217], v[16:19]
	v_mfma_f32_16x16x32_bf16 v[4:7], v[164:167], v[222:225], v[4:7]
	v_mfma_f32_16x16x32_bf16 v[0:3], v[172:175], v[222:225], v[0:3]
	s_setprio 0
	s_barrier
	s_add_i32 s37, 0, 0x18000
	s_add_i32 s63, 0, 0x1c000
	v_add_u32_e32 v156, s37, v179
	v_add_u32_e32 v172, s63, v179
	ds_read_b128 v[144:147], v156
	ds_read_b128 v[148:151], v156 offset:1024
	ds_read_b128 v[152:155], v156 offset:2048
	ds_read_b128 v[156:159], v156 offset:3072
	ds_read_b128 v[160:163], v172
	ds_read_b128 v[164:167], v172 offset:1024
	ds_read_b128 v[168:171], v172 offset:2048
	ds_read_b128 v[172:175], v172 offset:3072
	s_add_u32 s44, s44, 0x4000
	s_addc_u32 s45, s45, 0
	s_mov_b32 m0, s52
	v_lshl_add_u64 v[228:229], s[44:45], 0, v[128:129]
	ds_read_b128 v[192:195], v186 offset:32768
	ds_read_b128 v[196:199], v186 offset:33792
	ds_read_b128 v[202:205], v186 offset:34816
	ds_read_b128 v[206:209], v186 offset:35840
	ds_read_b128 v[210:213], v186 offset:36864
	ds_read_b128 v[214:217], v186 offset:37888
	ds_read_b128 v[218:221], v186 offset:38912
	ds_read_b128 v[222:225], v186 offset:39936
	global_load_lds_dwordx4 v[228:229], off
	v_lshl_add_u64 v[228:229], s[44:45], 0, v[132:133]
	s_mov_b32 m0, s53
	s_nop 0
	global_load_lds_dwordx4 v[228:229], off
	s_waitcnt vmcnt(12)
	s_waitcnt lgkmcnt(0)
	s_barrier
	s_setprio 1
	s_waitcnt lgkmcnt(0)
	v_mfma_f32_16x16x32_bf16 v[124:127], v[144:147], v[192:195], v[124:127]
	v_mfma_f32_16x16x32_bf16 v[120:123], v[152:155], v[192:195], v[120:123]
	v_mfma_f32_16x16x32_bf16 v[108:111], v[144:147], v[202:205], v[108:111]
	v_mfma_f32_16x16x32_bf16 v[104:107], v[152:155], v[202:205], v[104:107]
	v_mfma_f32_16x16x32_bf16 v[92:95], v[144:147], v[210:213], v[92:95]
	v_mfma_f32_16x16x32_bf16 v[88:91], v[152:155], v[210:213], v[88:91]
	v_mfma_f32_16x16x32_bf16 v[76:79], v[144:147], v[218:221], v[76:79]
	v_mfma_f32_16x16x32_bf16 v[72:75], v[152:155], v[218:221], v[72:75]
	v_mfma_f32_16x16x32_bf16 v[124:127], v[148:151], v[196:199], v[124:127]
	v_mfma_f32_16x16x32_bf16 v[120:123], v[156:159], v[196:199], v[120:123]
	v_mfma_f32_16x16x32_bf16 v[108:111], v[148:151], v[206:209], v[108:111]
	v_mfma_f32_16x16x32_bf16 v[104:107], v[156:159], v[206:209], v[104:107]
	v_mfma_f32_16x16x32_bf16 v[92:95], v[148:151], v[214:217], v[92:95]
	v_mfma_f32_16x16x32_bf16 v[88:91], v[156:159], v[214:217], v[88:91]
	v_mfma_f32_16x16x32_bf16 v[76:79], v[148:151], v[222:225], v[76:79]
	v_mfma_f32_16x16x32_bf16 v[72:75], v[156:159], v[222:225], v[72:75]
	s_setprio 0
	s_setprio 1
	v_mfma_f32_16x16x32_bf16 v[116:119], v[160:163], v[192:195], v[116:119]
	v_mfma_f32_16x16x32_bf16 v[112:115], v[168:171], v[192:195], v[112:115]
	v_mfma_f32_16x16x32_bf16 v[100:103], v[160:163], v[202:205], v[100:103]
	v_mfma_f32_16x16x32_bf16 v[96:99], v[168:171], v[202:205], v[96:99]
	v_mfma_f32_16x16x32_bf16 v[84:87], v[160:163], v[210:213], v[84:87]
	v_mfma_f32_16x16x32_bf16 v[80:83], v[168:171], v[210:213], v[80:83]
	v_mfma_f32_16x16x32_bf16 v[68:71], v[160:163], v[218:221], v[68:71]
	v_mfma_f32_16x16x32_bf16 v[64:67], v[168:171], v[218:221], v[64:67]
	v_mfma_f32_16x16x32_bf16 v[116:119], v[164:167], v[196:199], v[116:119]
	v_mfma_f32_16x16x32_bf16 v[112:115], v[172:175], v[196:199], v[112:115]
	v_mfma_f32_16x16x32_bf16 v[100:103], v[164:167], v[206:209], v[100:103]
	v_mfma_f32_16x16x32_bf16 v[96:99], v[172:175], v[206:209], v[96:99]
	v_mfma_f32_16x16x32_bf16 v[84:87], v[164:167], v[214:217], v[84:87]
	v_mfma_f32_16x16x32_bf16 v[80:83], v[172:175], v[214:217], v[80:83]
	v_mfma_f32_16x16x32_bf16 v[68:71], v[164:167], v[222:225], v[68:71]
	v_mfma_f32_16x16x32_bf16 v[64:67], v[172:175], v[222:225], v[64:67]
	s_setprio 0
	s_barrier
	s_add_i32 s37, s37, s49
	v_lshl_add_u64 v[176:177], v[176:177], 0, s[18:19]
	s_mov_b32 m0, s37
	ds_read_b128 v[192:195], v186 offset:49152
	ds_read_b128 v[196:199], v186 offset:50176
	ds_read_b128 v[202:205], v186 offset:51200
	ds_read_b128 v[206:209], v186 offset:52224
	ds_read_b128 v[210:213], v186 offset:53248
	ds_read_b128 v[214:217], v186 offset:54272
	ds_read_b128 v[218:221], v186 offset:55296
	ds_read_b128 v[222:225], v186 offset:56320
	global_load_lds_dwordx4 v[176:177], off
	s_add_i32 m0, s37, 0x2000
	s_add_u32 s42, s42, 0x100080
	v_lshl_add_u64 v[176:177], v[226:227], 0, s[18:19]
	s_addc_u32 s43, s43, 0
	s_add_i32 s37, s63, s49
	global_load_lds_dwordx4 v[176:177], off
	v_lshl_add_u64 v[176:177], s[42:43], 0, v[130:131]
	s_mov_b32 m0, s37
	s_nop 0
	global_load_lds_dwordx4 v[176:177], off
	v_lshl_add_u64 v[176:177], s[42:43], 0, v[134:135]
	s_add_i32 m0, s37, 0x2000
	s_nop 0
	global_load_lds_dwordx4 v[176:177], off
	v_lshl_add_u64 v[176:177], s[40:41], 0, v[128:129]
	s_mov_b32 m0, s57
	s_nop 0
	global_load_lds_dwordx4 v[176:177], off
	v_lshl_add_u64 v[176:177], s[40:41], 0, v[132:133]
	s_mov_b32 m0, s58
	s_nop 0
	global_load_lds_dwordx4 v[176:177], off
	s_waitcnt vmcnt(12)
	s_waitcnt lgkmcnt(0)
	s_barrier
	s_setprio 1
	s_waitcnt lgkmcnt(0)
	v_mfma_f32_16x16x32_bf16 v[60:63], v[144:147], v[192:195], v[60:63]
	v_mfma_f32_16x16x32_bf16 v[56:59], v[152:155], v[192:195], v[56:59]
	v_mfma_f32_16x16x32_bf16 v[44:47], v[144:147], v[202:205], v[44:47]
	v_mfma_f32_16x16x32_bf16 v[40:43], v[152:155], v[202:205], v[40:43]
	v_mfma_f32_16x16x32_bf16 v[28:31], v[144:147], v[210:213], v[28:31]
	v_mfma_f32_16x16x32_bf16 v[24:27], v[152:155], v[210:213], v[24:27]
	v_mfma_f32_16x16x32_bf16 v[12:15], v[144:147], v[218:221], v[12:15]
	v_mfma_f32_16x16x32_bf16 v[8:11], v[152:155], v[218:221], v[8:11]
	v_mfma_f32_16x16x32_bf16 v[60:63], v[148:151], v[196:199], v[60:63]
	v_mfma_f32_16x16x32_bf16 v[56:59], v[156:159], v[196:199], v[56:59]
	v_mfma_f32_16x16x32_bf16 v[44:47], v[148:151], v[206:209], v[44:47]
	v_mfma_f32_16x16x32_bf16 v[40:43], v[156:159], v[206:209], v[40:43]
	v_mfma_f32_16x16x32_bf16 v[28:31], v[148:151], v[214:217], v[28:31]
	v_mfma_f32_16x16x32_bf16 v[24:27], v[156:159], v[214:217], v[24:27]
	v_mfma_f32_16x16x32_bf16 v[12:15], v[148:151], v[222:225], v[12:15]
	v_mfma_f32_16x16x32_bf16 v[8:11], v[156:159], v[222:225], v[8:11]
	s_setprio 0
	s_setprio 1
	v_mfma_f32_16x16x32_bf16 v[52:55], v[160:163], v[192:195], v[52:55]
	v_mfma_f32_16x16x32_bf16 v[48:51], v[168:171], v[192:195], v[48:51]
	v_mfma_f32_16x16x32_bf16 v[36:39], v[160:163], v[202:205], v[36:39]
	v_mfma_f32_16x16x32_bf16 v[32:35], v[168:171], v[202:205], v[32:35]
	v_mfma_f32_16x16x32_bf16 v[20:23], v[160:163], v[210:213], v[20:23]
	v_mfma_f32_16x16x32_bf16 v[16:19], v[168:171], v[210:213], v[16:19]
	v_mfma_f32_16x16x32_bf16 v[4:7], v[160:163], v[218:221], v[4:7]
	v_mfma_f32_16x16x32_bf16 v[0:3], v[168:171], v[218:221], v[0:3]
	v_mfma_f32_16x16x32_bf16 v[52:55], v[164:167], v[196:199], v[52:55]
	v_mfma_f32_16x16x32_bf16 v[48:51], v[172:175], v[196:199], v[48:51]
	v_mfma_f32_16x16x32_bf16 v[36:39], v[164:167], v[206:209], v[36:39]
	v_mfma_f32_16x16x32_bf16 v[32:35], v[172:175], v[206:209], v[32:35]
	v_mfma_f32_16x16x32_bf16 v[20:23], v[164:167], v[214:217], v[20:23]
	v_mfma_f32_16x16x32_bf16 v[16:19], v[172:175], v[214:217], v[16:19]
	v_mfma_f32_16x16x32_bf16 v[4:7], v[164:167], v[222:225], v[4:7]
	v_mfma_f32_16x16x32_bf16 v[0:3], v[172:175], v[222:225], v[0:3]
	s_setprio 0
	s_barrier
	s_add_i32 s33, s33, 2
	s_add_u32 s11, s11, 0x100
	s_addc_u32 s29, s29, 0
	s_add_u32 s38, s38, 0x10000
	s_addc_u32 s39, s39, 0
	s_and_b64 vcc, exec, s[20:21]
	s_cbranch_vccz .LBB0_793
	s_barrier
.LBB0_793:
	s_lshl_b32 s11, s10, 8
	v_add_u32_e32 v176, s11, v178
	v_lshl_or_b32 v177, s36, 8, v180
	v_lshlrev_b32_e32 v176, 11, v176
	v_lshl_add_u32 v176, v177, 1, v176
	s_add_u32 s38, s24, 0x10000
	s_addc_u32 s39, s25, 0
	global_load_dwordx4 v[144:147], v176, s[38:39]
	global_load_dwordx4 v[148:151], v176, s[38:39] offset:256
	s_add_u32 s38, s24, 0x18000
	s_addc_u32 s39, s25, 0
	global_load_dwordx4 v[152:155], v176, s[38:39]
	global_load_dwordx4 v[156:159], v176, s[38:39] offset:256
	s_add_u32 s38, s24, 0x40000
	s_addc_u32 s39, s25, 0
	global_load_dwordx4 v[160:163], v176, s[38:39]
	global_load_dwordx4 v[164:167], v176, s[38:39] offset:256
	s_add_u32 s38, s24, 0x48000
	s_addc_u32 s39, s25, 0
	global_load_dwordx4 v[168:171], v176, s[38:39]
	global_load_dwordx4 v[172:175], v176, s[38:39] offset:256
	s_add_u32 s38, s24, 0x50000
	s_addc_u32 s39, s25, 0
	global_load_dwordx4 v[192:195], v176, s[38:39]
	global_load_dwordx4 v[196:199], v176, s[38:39] offset:256
	v_xor_b32_e32 v201, 16, v187
	v_xor_b32_e32 v249, 32, v187
	v_lshlrev_b32_e32 v201, 2, v201
	v_lshlrev_b32_e32 v249, 2, v249
	s_mov_b32 s41, 0xffff0000
	s_waitcnt vmcnt(18)
	v_lshlrev_b32_e32 v210, 16, v230
	v_and_b32_e32 v211, s41, v230
	v_lshlrev_b32_e32 v212, 16, v231
	v_and_b32_e32 v213, s41, v231
	v_lshlrev_b32_e32 v214, 16, v232
	v_and_b32_e32 v215, s41, v232
	v_lshlrev_b32_e32 v216, 16, v233
	v_and_b32_e32 v217, s41, v233
	v_pk_add_f32 v[124:125], v[124:125], v[210:211]
	v_pk_add_f32 v[126:127], v[126:127], v[212:213]
	v_pk_add_f32 v[120:121], v[120:121], v[214:215]
	v_pk_add_f32 v[122:123], v[122:123], v[216:217]
	v_lshlrev_b32_e32 v218, 16, v234
	v_and_b32_e32 v219, s41, v234
	v_lshlrev_b32_e32 v220, 16, v235
	v_and_b32_e32 v221, s41, v235
	v_lshlrev_b32_e32 v246, 16, v236
	v_and_b32_e32 v247, s41, v236
	v_lshlrev_b32_e32 v250, 16, v237
	v_and_b32_e32 v251, s41, v237
	v_pk_add_f32 v[116:117], v[116:117], v[218:219]
	v_pk_add_f32 v[118:119], v[118:119], v[220:221]
	v_pk_add_f32 v[112:113], v[112:113], v[246:247]
	v_pk_add_f32 v[114:115], v[114:115], v[250:251]
	v_pk_mul_f32 v[252:253], v[124:125], v[124:125]
	v_pk_mul_f32 v[254:255], v[126:127], v[126:127]
	v_pk_fma_f32 v[252:253], v[120:121], v[120:121], v[252:253]
	v_pk_fma_f32 v[254:255], v[122:123], v[122:123], v[254:255]
	v_pk_fma_f32 v[252:253], v[116:117], v[116:117], v[252:253]
	v_pk_fma_f32 v[254:255], v[118:119], v[118:119], v[254:255]
	v_pk_fma_f32 v[252:253], v[112:113], v[112:113], v[252:253]
	v_pk_fma_f32 v[254:255], v[114:115], v[114:115], v[254:255]
	v_pk_add_f32 v[252:253], v[252:253], v[254:255]
	s_nop 0
	v_add_f32_e32 v202, v252, v253
	v_lshlrev_b32_e32 v210, 16, v238
	v_and_b32_e32 v211, s41, v238
	v_lshlrev_b32_e32 v212, 16, v239
	v_and_b32_e32 v213, s41, v239
	v_lshlrev_b32_e32 v214, 16, v240
	v_and_b32_e32 v215, s41, v240
	v_lshlrev_b32_e32 v216, 16, v241
	v_and_b32_e32 v217, s41, v241
	v_pk_add_f32 v[108:109], v[108:109], v[210:211]
	v_pk_add_f32 v[110:111], v[110:111], v[212:213]
	v_pk_add_f32 v[104:105], v[104:105], v[214:215]
	v_pk_add_f32 v[106:107], v[106:107], v[216:217]
	v_lshlrev_b32_e32 v218, 16, v242
	v_and_b32_e32 v219, s41, v242
	v_lshlrev_b32_e32 v220, 16, v243
	v_and_b32_e32 v221, s41, v243
	v_lshlrev_b32_e32 v246, 16, v244
	v_and_b32_e32 v247, s41, v244
	v_lshlrev_b32_e32 v250, 16, v245
	v_and_b32_e32 v251, s41, v245
	v_pk_add_f32 v[100:101], v[100:101], v[218:219]
	v_pk_add_f32 v[102:103], v[102:103], v[220:221]
	v_pk_add_f32 v[96:97], v[96:97], v[246:247]
	v_pk_add_f32 v[98:99], v[98:99], v[250:251]
	v_pk_mul_f32 v[252:253], v[108:109], v[108:109]
	v_pk_mul_f32 v[254:255], v[110:111], v[110:111]
	v_pk_fma_f32 v[252:253], v[104:105], v[104:105], v[252:253]
	v_pk_fma_f32 v[254:255], v[106:107], v[106:107], v[254:255]
	v_pk_fma_f32 v[252:253], v[100:101], v[100:101], v[252:253]
	v_pk_fma_f32 v[254:255], v[102:103], v[102:103], v[254:255]
	v_pk_fma_f32 v[252:253], v[96:97], v[96:97], v[252:253]
	v_pk_fma_f32 v[254:255], v[98:99], v[98:99], v[254:255]
	v_pk_add_f32 v[252:253], v[252:253], v[254:255]
	s_nop 0
	v_add_f32_e32 v203, v252, v253
	s_waitcnt vmcnt(8)
	v_lshlrev_b32_e32 v210, 16, v144
	v_and_b32_e32 v211, s41, v144
	v_lshlrev_b32_e32 v212, 16, v145
	v_and_b32_e32 v213, s41, v145
	v_lshlrev_b32_e32 v214, 16, v146
	v_and_b32_e32 v215, s41, v146
	v_lshlrev_b32_e32 v216, 16, v147
	v_and_b32_e32 v217, s41, v147
	v_pk_add_f32 v[92:93], v[92:93], v[210:211]
	v_pk_add_f32 v[94:95], v[94:95], v[212:213]
	v_pk_add_f32 v[88:89], v[88:89], v[214:215]
	v_pk_add_f32 v[90:91], v[90:91], v[216:217]
	v_lshlrev_b32_e32 v218, 16, v148
	v_and_b32_e32 v219, s41, v148
	v_lshlrev_b32_e32 v220, 16, v149
	v_and_b32_e32 v221, s41, v149
	v_lshlrev_b32_e32 v246, 16, v150
	v_and_b32_e32 v247, s41, v150
	v_lshlrev_b32_e32 v250, 16, v151
	v_and_b32_e32 v251, s41, v151
	v_pk_add_f32 v[84:85], v[84:85], v[218:219]
	v_pk_add_f32 v[86:87], v[86:87], v[220:221]
	v_pk_add_f32 v[80:81], v[80:81], v[246:247]
	v_pk_add_f32 v[82:83], v[82:83], v[250:251]
	s_add_u32 s38, s24, 0x58000
	s_addc_u32 s39, s25, 0
	global_load_dwordx4 v[144:147], v176, s[38:39]
	global_load_dwordx4 v[148:151], v176, s[38:39] offset:256
	v_pk_mul_f32 v[252:253], v[92:93], v[92:93]
	v_pk_mul_f32 v[254:255], v[94:95], v[94:95]
	v_pk_fma_f32 v[252:253], v[88:89], v[88:89], v[252:253]
	v_pk_fma_f32 v[254:255], v[90:91], v[90:91], v[254:255]
	v_pk_fma_f32 v[252:253], v[84:85], v[84:85], v[252:253]
	v_pk_fma_f32 v[254:255], v[86:87], v[86:87], v[254:255]
	v_pk_fma_f32 v[252:253], v[80:81], v[80:81], v[252:253]
	v_pk_fma_f32 v[254:255], v[82:83], v[82:83], v[254:255]
	v_pk_add_f32 v[252:253], v[252:253], v[254:255]
	s_nop 0
	v_add_f32_e32 v204, v252, v253
	s_waitcnt vmcnt(8)
	v_lshlrev_b32_e32 v210, 16, v152
	v_and_b32_e32 v211, s41, v152
	v_lshlrev_b32_e32 v212, 16, v153
	v_and_b32_e32 v213, s41, v153
	v_lshlrev_b32_e32 v214, 16, v154
	v_and_b32_e32 v215, s41, v154
	v_lshlrev_b32_e32 v216, 16, v155
	v_and_b32_e32 v217, s41, v155
	v_pk_add_f32 v[76:77], v[76:77], v[210:211]
	v_pk_add_f32 v[78:79], v[78:79], v[212:213]
	v_pk_add_f32 v[72:73], v[72:73], v[214:215]
	v_pk_add_f32 v[74:75], v[74:75], v[216:217]
	v_lshlrev_b32_e32 v218, 16, v156
	v_and_b32_e32 v219, s41, v156
	v_lshlrev_b32_e32 v220, 16, v157
	v_and_b32_e32 v221, s41, v157
	v_lshlrev_b32_e32 v246, 16, v158
	v_and_b32_e32 v247, s41, v158
	v_lshlrev_b32_e32 v250, 16, v159
	v_and_b32_e32 v251, s41, v159
	v_pk_add_f32 v[68:69], v[68:69], v[218:219]
	v_pk_add_f32 v[70:71], v[70:71], v[220:221]
	v_pk_add_f32 v[64:65], v[64:65], v[246:247]
	v_pk_add_f32 v[66:67], v[66:67], v[250:251]
	v_pk_mul_f32 v[252:253], v[76:77], v[76:77]
	v_pk_mul_f32 v[254:255], v[78:79], v[78:79]
	v_pk_fma_f32 v[252:253], v[72:73], v[72:73], v[252:253]
	v_pk_fma_f32 v[254:255], v[74:75], v[74:75], v[254:255]
	v_pk_fma_f32 v[252:253], v[68:69], v[68:69], v[252:253]
	v_pk_fma_f32 v[254:255], v[70:71], v[70:71], v[254:255]
	v_pk_fma_f32 v[252:253], v[64:65], v[64:65], v[252:253]
	v_pk_fma_f32 v[254:255], v[66:67], v[66:67], v[254:255]
	v_pk_add_f32 v[252:253], v[252:253], v[254:255]
	s_nop 0
	v_add_f32_e32 v205, v252, v253
	s_waitcnt vmcnt(6)
	v_lshlrev_b32_e32 v210, 16, v160
	v_and_b32_e32 v211, s41, v160
	v_lshlrev_b32_e32 v212, 16, v161
	v_and_b32_e32 v213, s41, v161
	v_lshlrev_b32_e32 v214, 16, v162
	v_and_b32_e32 v215, s41, v162
	v_lshlrev_b32_e32 v216, 16, v163
	v_and_b32_e32 v217, s41, v163
	v_pk_add_f32 v[60:61], v[60:61], v[210:211]
	v_pk_add_f32 v[62:63], v[62:63], v[212:213]
	v_pk_add_f32 v[56:57], v[56:57], v[214:215]
	v_pk_add_f32 v[58:59], v[58:59], v[216:217]
	v_lshlrev_b32_e32 v218, 16, v164
	v_and_b32_e32 v219, s41, v164
	v_lshlrev_b32_e32 v220, 16, v165
	v_and_b32_e32 v221, s41, v165
	v_lshlrev_b32_e32 v246, 16, v166
	v_and_b32_e32 v247, s41, v166
	v_lshlrev_b32_e32 v250, 16, v167
	v_and_b32_e32 v251, s41, v167
	v_pk_add_f32 v[52:53], v[52:53], v[218:219]
	v_pk_add_f32 v[54:55], v[54:55], v[220:221]
	v_pk_add_f32 v[48:49], v[48:49], v[246:247]
	v_pk_add_f32 v[50:51], v[50:51], v[250:251]
	v_pk_mul_f32 v[252:253], v[60:61], v[60:61]
	v_pk_mul_f32 v[254:255], v[62:63], v[62:63]
	v_pk_fma_f32 v[252:253], v[56:57], v[56:57], v[252:253]
	v_pk_fma_f32 v[254:255], v[58:59], v[58:59], v[254:255]
	v_pk_fma_f32 v[252:253], v[52:53], v[52:53], v[252:253]
	v_pk_fma_f32 v[254:255], v[54:55], v[54:55], v[254:255]
	v_pk_fma_f32 v[252:253], v[48:49], v[48:49], v[252:253]
	v_pk_fma_f32 v[254:255], v[50:51], v[50:51], v[254:255]
	v_pk_add_f32 v[252:253], v[252:253], v[254:255]
	s_nop 0
	v_add_f32_e32 v206, v252, v253
	s_waitcnt vmcnt(4)
	v_lshlrev_b32_e32 v210, 16, v168
	v_and_b32_e32 v211, s41, v168
	v_lshlrev_b32_e32 v212, 16, v169
	v_and_b32_e32 v213, s41, v169
	v_lshlrev_b32_e32 v214, 16, v170
	v_and_b32_e32 v215, s41, v170
	v_lshlrev_b32_e32 v216, 16, v171
	v_and_b32_e32 v217, s41, v171
	v_pk_add_f32 v[44:45], v[44:45], v[210:211]
	v_pk_add_f32 v[46:47], v[46:47], v[212:213]
	v_pk_add_f32 v[40:41], v[40:41], v[214:215]
	v_pk_add_f32 v[42:43], v[42:43], v[216:217]
	v_lshlrev_b32_e32 v218, 16, v172
	v_and_b32_e32 v219, s41, v172
	v_lshlrev_b32_e32 v220, 16, v173
	v_and_b32_e32 v221, s41, v173
	v_lshlrev_b32_e32 v246, 16, v174
	v_and_b32_e32 v247, s41, v174
	v_lshlrev_b32_e32 v250, 16, v175
	v_and_b32_e32 v251, s41, v175
	v_pk_add_f32 v[36:37], v[36:37], v[218:219]
	v_pk_add_f32 v[38:39], v[38:39], v[220:221]
	v_pk_add_f32 v[32:33], v[32:33], v[246:247]
	v_pk_add_f32 v[34:35], v[34:35], v[250:251]
	v_pk_mul_f32 v[252:253], v[44:45], v[44:45]
	v_pk_mul_f32 v[254:255], v[46:47], v[46:47]
	v_pk_fma_f32 v[252:253], v[40:41], v[40:41], v[252:253]
	v_pk_fma_f32 v[254:255], v[42:43], v[42:43], v[254:255]
	v_pk_fma_f32 v[252:253], v[36:37], v[36:37], v[252:253]
	v_pk_fma_f32 v[254:255], v[38:39], v[38:39], v[254:255]
	v_pk_fma_f32 v[252:253], v[32:33], v[32:33], v[252:253]
	v_pk_fma_f32 v[254:255], v[34:35], v[34:35], v[254:255]
	v_pk_add_f32 v[252:253], v[252:253], v[254:255]
	s_nop 0
	v_add_f32_e32 v207, v252, v253
	s_waitcnt vmcnt(2)
	v_lshlrev_b32_e32 v210, 16, v192
	v_and_b32_e32 v211, s41, v192
	v_lshlrev_b32_e32 v212, 16, v193
	v_and_b32_e32 v213, s41, v193
	v_lshlrev_b32_e32 v214, 16, v194
	v_and_b32_e32 v215, s41, v194
	v_lshlrev_b32_e32 v216, 16, v195
	v_and_b32_e32 v217, s41, v195
	v_pk_add_f32 v[28:29], v[28:29], v[210:211]
	v_pk_add_f32 v[30:31], v[30:31], v[212:213]
	v_pk_add_f32 v[24:25], v[24:25], v[214:215]
	v_pk_add_f32 v[26:27], v[26:27], v[216:217]
	v_lshlrev_b32_e32 v218, 16, v196
	v_and_b32_e32 v219, s41, v196
	v_lshlrev_b32_e32 v220, 16, v197
	v_and_b32_e32 v221, s41, v197
	v_lshlrev_b32_e32 v246, 16, v198
	v_and_b32_e32 v247, s41, v198
	v_lshlrev_b32_e32 v250, 16, v199
	v_and_b32_e32 v251, s41, v199
	v_pk_add_f32 v[20:21], v[20:21], v[218:219]
	v_pk_add_f32 v[22:23], v[22:23], v[220:221]
	v_pk_add_f32 v[16:17], v[16:17], v[246:247]
	v_pk_add_f32 v[18:19], v[18:19], v[250:251]
	v_pk_mul_f32 v[252:253], v[28:29], v[28:29]
	v_pk_mul_f32 v[254:255], v[30:31], v[30:31]
	v_pk_fma_f32 v[252:253], v[24:25], v[24:25], v[252:253]
	v_pk_fma_f32 v[254:255], v[26:27], v[26:27], v[254:255]
	v_pk_fma_f32 v[252:253], v[20:21], v[20:21], v[252:253]
	v_pk_fma_f32 v[254:255], v[22:23], v[22:23], v[254:255]
	v_pk_fma_f32 v[252:253], v[16:17], v[16:17], v[252:253]
	v_pk_fma_f32 v[254:255], v[18:19], v[18:19], v[254:255]
	v_pk_add_f32 v[252:253], v[252:253], v[254:255]
	s_nop 0
	v_add_f32_e32 v208, v252, v253
	s_waitcnt vmcnt(0)
	v_lshlrev_b32_e32 v210, 16, v144
	v_and_b32_e32 v211, s41, v144
	v_lshlrev_b32_e32 v212, 16, v145
	v_and_b32_e32 v213, s41, v145
	v_lshlrev_b32_e32 v214, 16, v146
	v_and_b32_e32 v215, s41, v146
	v_lshlrev_b32_e32 v216, 16, v147
	v_and_b32_e32 v217, s41, v147
	v_pk_add_f32 v[172:173], v[12:13], v[210:211]
	v_pk_add_f32 v[174:175], v[14:15], v[212:213]
	v_pk_add_f32 v[168:169], v[8:9], v[214:215]
	v_pk_add_f32 v[170:171], v[10:11], v[216:217]
	v_lshlrev_b32_e32 v218, 16, v148
	v_and_b32_e32 v219, s41, v148
	v_lshlrev_b32_e32 v220, 16, v149
	v_and_b32_e32 v221, s41, v149
	v_lshlrev_b32_e32 v246, 16, v150
	v_and_b32_e32 v247, s41, v150
	v_lshlrev_b32_e32 v250, 16, v151
	v_and_b32_e32 v251, s41, v151
	v_pk_add_f32 v[164:165], v[4:5], v[218:219]
	v_pk_add_f32 v[166:167], v[6:7], v[220:221]
	v_pk_add_f32 v[160:161], v[0:1], v[246:247]
	v_pk_add_f32 v[162:163], v[2:3], v[250:251]
	v_pk_mul_f32 v[252:253], v[172:173], v[172:173]
	v_pk_mul_f32 v[254:255], v[174:175], v[174:175]
	v_pk_fma_f32 v[252:253], v[168:169], v[168:169], v[252:253]
	v_pk_fma_f32 v[254:255], v[170:171], v[170:171], v[254:255]
	v_pk_fma_f32 v[252:253], v[164:165], v[164:165], v[252:253]
	v_pk_fma_f32 v[254:255], v[166:167], v[166:167], v[254:255]
	v_pk_fma_f32 v[252:253], v[160:161], v[160:161], v[252:253]
	v_pk_fma_f32 v[254:255], v[162:163], v[162:163], v[254:255]
	v_pk_add_f32 v[252:253], v[252:253], v[254:255]
	s_nop 0
	v_add_f32_e32 v209, v252, v253
	ds_bpermute_b32 v144, v201, v202
	ds_bpermute_b32 v145, v201, v203
	ds_bpermute_b32 v146, v201, v204
	ds_bpermute_b32 v147, v201, v205
	ds_bpermute_b32 v148, v201, v206
	ds_bpermute_b32 v149, v201, v207
	ds_bpermute_b32 v150, v201, v208
	ds_bpermute_b32 v151, v201, v209
	s_waitcnt lgkmcnt(7)
	v_add_f32_e32 v202, v202, v144
	s_waitcnt lgkmcnt(6)
	v_add_f32_e32 v203, v203, v145
	s_waitcnt lgkmcnt(5)
	v_add_f32_e32 v204, v204, v146
	s_waitcnt lgkmcnt(4)
	v_add_f32_e32 v205, v205, v147
	s_waitcnt lgkmcnt(3)
	v_add_f32_e32 v206, v206, v148
	s_waitcnt lgkmcnt(2)
	v_add_f32_e32 v207, v207, v149
	s_waitcnt lgkmcnt(1)
	v_add_f32_e32 v208, v208, v150
	s_waitcnt lgkmcnt(0)
	v_add_f32_e32 v209, v209, v151
	ds_bpermute_b32 v144, v249, v202
	ds_bpermute_b32 v145, v249, v203
	ds_bpermute_b32 v146, v249, v204
	ds_bpermute_b32 v147, v249, v205
	ds_bpermute_b32 v148, v249, v206
	ds_bpermute_b32 v149, v249, v207
	ds_bpermute_b32 v150, v249, v208
	ds_bpermute_b32 v151, v249, v209
	s_waitcnt lgkmcnt(7)
	v_add_f32_e32 v202, v202, v144
	s_waitcnt lgkmcnt(6)
	v_add_f32_e32 v203, v203, v145
	s_waitcnt lgkmcnt(5)
	v_add_f32_e32 v204, v204, v146
	s_waitcnt lgkmcnt(4)
	v_add_f32_e32 v205, v205, v147
	s_waitcnt lgkmcnt(3)
	v_add_f32_e32 v206, v206, v148
	s_waitcnt lgkmcnt(2)
	v_add_f32_e32 v207, v207, v149
	s_waitcnt lgkmcnt(1)
	v_add_f32_e32 v208, v208, v150
	s_waitcnt lgkmcnt(0)
	v_add_f32_e32 v209, v209, v151
	v_lshl_or_b32 v177, s36, 8, v180
	v_lshlrev_b32_e32 v177, 2, v177
	global_load_dwordx4 v[144:147], v177, s[84:85]
	global_load_dwordx4 v[148:151], v177, s[84:85] offset:16
	global_load_dwordx4 v[152:155], v177, s[84:85] offset:512
	global_load_dwordx4 v[156:159], v177, s[84:85] offset:528
	s_and_saveexec_b64 s[38:39], s[0:1]
	ds_write_b32 v191, v202
	ds_write_b32 v191, v203 offset:256
	ds_write_b32 v191, v204 offset:512
	ds_write_b32 v191, v205 offset:768
	ds_write_b32 v191, v206 offset:2048
	ds_write_b32 v191, v207 offset:2304
	ds_write_b32 v191, v208 offset:2560
	ds_write_b32 v191, v209 offset:2816
	s_or_b64 exec, exec, s[38:39]
	s_waitcnt lgkmcnt(0)
	s_barrier
	v_add_u32_e32 v0, s11, v181
	s_waitcnt lgkmcnt(0)
	v_ashrrev_i32_e32 v1, 31, v0
	s_and_saveexec_b64 s[38:39], s[8:9]
	s_cbranch_execz .LBB0_811
	ds_read_b128 v[2:5], v188
	s_ashr_i32 s37, s36, 31
	v_lshl_add_u64 v[6:7], v[0:1], 4, s[26:27]
	v_lshl_add_u64 v[6:7], s[36:37], 2, v[6:7]
	s_waitcnt lgkmcnt(0)
	v_mov_b32_e32 v8, v3
	v_mov_b32_e32 v9, v4
	v_mov_b32_e32 v3, v5
	v_pk_add_f32 v[2:3], v[8:9], v[2:3]
	s_nop 0
	v_pk_add_f32 v[2:3], v[2:3], v[2:3] op_sel:[0,1] op_sel_hi:[1,0]
	global_store_dword v[6:7], v2, off sc1

.LBB0_826:
	s_or_b64 exec, exec, s[36:37]
	s_waitcnt vmcnt(0) lgkmcnt(0)
	s_barrier
	ds_read2_b32 v[192:193], v183 offset1:16
	ds_read2_b32 v[194:195], v183 offset0:32 offset1:48
	ds_read2_b32 v[196:197], v183 offset0:128 offset1:144
	ds_read2_b32 v[198:199], v183 offset0:160 offset1:176
	v_lshlrev_b32_e32 v177, 1, v176
	s_waitcnt lgkmcnt(3)
	s_mov_b64 s[38:39], s[86:87]
	v_pk_mul_f32 v[124:125], v[124:125], v[192:193] op_sel:[0,0] op_sel_hi:[1,0]
	v_pk_mul_f32 v[126:127], v[126:127], v[192:193] op_sel:[0,0] op_sel_hi:[1,0]
	v_pk_mul_f32 v[120:121], v[120:121], v[192:193] op_sel:[0,0] op_sel_hi:[1,0]
	v_pk_mul_f32 v[122:123], v[122:123], v[192:193] op_sel:[0,0] op_sel_hi:[1,0]
	v_pk_mul_f32 v[124:125], v[124:125], v[144:145]
	v_pk_mul_f32 v[126:127], v[126:127], v[146:147]
	v_pk_mul_f32 v[120:121], v[120:121], v[148:149]
	v_pk_mul_f32 v[122:123], v[122:123], v[150:151]
	global_store_dwordx4 v177, v[124:127], s[38:39]
	global_store_dwordx4 v177, v[120:123], s[38:39] offset:16
	v_pk_mul_f32 v[116:117], v[116:117], v[192:193] op_sel:[0,0] op_sel_hi:[1,0]
	v_pk_mul_f32 v[118:119], v[118:119], v[192:193] op_sel:[0,0] op_sel_hi:[1,0]
	v_pk_mul_f32 v[112:113], v[112:113], v[192:193] op_sel:[0,0] op_sel_hi:[1,0]
	v_pk_mul_f32 v[114:115], v[114:115], v[192:193] op_sel:[0,0] op_sel_hi:[1,0]
	v_pk_mul_f32 v[116:117], v[116:117], v[152:153]
	v_pk_mul_f32 v[118:119], v[118:119], v[154:155]
	v_pk_mul_f32 v[112:113], v[112:113], v[156:157]
	v_pk_mul_f32 v[114:115], v[114:115], v[158:159]
	global_store_dwordx4 v177, v[116:119], s[38:39] offset:512
	global_store_dwordx4 v177, v[112:115], s[38:39] offset:528
	s_add_u32 s38, s86, 0x10000
	s_addc_u32 s39, s87, 0
	v_pk_mul_f32 v[108:109], v[108:109], v[192:193] op_sel:[0,1] op_sel_hi:[1,1]
	v_pk_mul_f32 v[110:111], v[110:111], v[192:193] op_sel:[0,1] op_sel_hi:[1,1]
	v_pk_mul_f32 v[104:105], v[104:105], v[192:193] op_sel:[0,1] op_sel_hi:[1,1]
	v_pk_mul_f32 v[106:107], v[106:107], v[192:193] op_sel:[0,1] op_sel_hi:[1,1]
	v_pk_mul_f32 v[108:109], v[108:109], v[144:145]
	v_pk_mul_f32 v[110:111], v[110:111], v[146:147]
	v_pk_mul_f32 v[104:105], v[104:105], v[148:149]
	v_pk_mul_f32 v[106:107], v[106:107], v[150:151]
	global_store_dwordx4 v177, v[108:111], s[38:39]
	global_store_dwordx4 v177, v[104:107], s[38:39] offset:16
	v_pk_mul_f32 v[100:101], v[100:101], v[192:193] op_sel:[0,1] op_sel_hi:[1,1]
	v_pk_mul_f32 v[102:103], v[102:103], v[192:193] op_sel:[0,1] op_sel_hi:[1,1]
	v_pk_mul_f32 v[96:97], v[96:97], v[192:193] op_sel:[0,1] op_sel_hi:[1,1]
	v_pk_mul_f32 v[98:99], v[98:99], v[192:193] op_sel:[0,1] op_sel_hi:[1,1]
	v_pk_mul_f32 v[100:101], v[100:101], v[152:153]
	v_pk_mul_f32 v[102:103], v[102:103], v[154:155]
	v_pk_mul_f32 v[96:97], v[96:97], v[156:157]
	v_pk_mul_f32 v[98:99], v[98:99], v[158:159]
	global_store_dwordx4 v177, v[100:103], s[38:39] offset:512
	global_store_dwordx4 v177, v[96:99], s[38:39] offset:528
	s_waitcnt lgkmcnt(2)
	s_add_u32 s38, s86, 0x20000
	s_addc_u32 s39, s87, 0
	v_pk_mul_f32 v[92:93], v[92:93], v[194:195] op_sel:[0,0] op_sel_hi:[1,0]
	v_pk_mul_f32 v[94:95], v[94:95], v[194:195] op_sel:[0,0] op_sel_hi:[1,0]
	v_pk_mul_f32 v[88:89], v[88:89], v[194:195] op_sel:[0,0] op_sel_hi:[1,0]
	v_pk_mul_f32 v[90:91], v[90:91], v[194:195] op_sel:[0,0] op_sel_hi:[1,0]
	v_pk_mul_f32 v[92:93], v[92:93], v[144:145]
	v_pk_mul_f32 v[94:95], v[94:95], v[146:147]
	v_pk_mul_f32 v[88:89], v[88:89], v[148:149]
	v_pk_mul_f32 v[90:91], v[90:91], v[150:151]
	global_store_dwordx4 v177, v[92:95], s[38:39]
	global_store_dwordx4 v177, v[88:91], s[38:39] offset:16
	v_pk_mul_f32 v[84:85], v[84:85], v[194:195] op_sel:[0,0] op_sel_hi:[1,0]
	v_pk_mul_f32 v[86:87], v[86:87], v[194:195] op_sel:[0,0] op_sel_hi:[1,0]
	v_pk_mul_f32 v[80:81], v[80:81], v[194:195] op_sel:[0,0] op_sel_hi:[1,0]
	v_pk_mul_f32 v[82:83], v[82:83], v[194:195] op_sel:[0,0] op_sel_hi:[1,0]
	v_pk_mul_f32 v[84:85], v[84:85], v[152:153]
	v_pk_mul_f32 v[86:87], v[86:87], v[154:155]
	v_pk_mul_f32 v[80:81], v[80:81], v[156:157]
	v_pk_mul_f32 v[82:83], v[82:83], v[158:159]
	global_store_dwordx4 v177, v[84:87], s[38:39] offset:512
	global_store_dwordx4 v177, v[80:83], s[38:39] offset:528
	s_add_u32 s38, s86, 0x30000
	s_addc_u32 s39, s87, 0
	v_pk_mul_f32 v[76:77], v[76:77], v[194:195] op_sel:[0,1] op_sel_hi:[1,1]
	v_pk_mul_f32 v[78:79], v[78:79], v[194:195] op_sel:[0,1] op_sel_hi:[1,1]
	v_pk_mul_f32 v[72:73], v[72:73], v[194:195] op_sel:[0,1] op_sel_hi:[1,1]
	v_pk_mul_f32 v[74:75], v[74:75], v[194:195] op_sel:[0,1] op_sel_hi:[1,1]
	v_pk_mul_f32 v[76:77], v[76:77], v[144:145]
	v_pk_mul_f32 v[78:79], v[78:79], v[146:147]
	v_pk_mul_f32 v[72:73], v[72:73], v[148:149]
	v_pk_mul_f32 v[74:75], v[74:75], v[150:151]
	global_store_dwordx4 v177, v[76:79], s[38:39]
	global_store_dwordx4 v177, v[72:75], s[38:39] offset:16
	v_pk_mul_f32 v[68:69], v[68:69], v[194:195] op_sel:[0,1] op_sel_hi:[1,1]
	v_pk_mul_f32 v[70:71], v[70:71], v[194:195] op_sel:[0,1] op_sel_hi:[1,1]
	v_pk_mul_f32 v[64:65], v[64:65], v[194:195] op_sel:[0,1] op_sel_hi:[1,1]
	v_pk_mul_f32 v[66:67], v[66:67], v[194:195] op_sel:[0,1] op_sel_hi:[1,1]
	v_pk_mul_f32 v[68:69], v[68:69], v[152:153]
	v_pk_mul_f32 v[70:71], v[70:71], v[154:155]
	v_pk_mul_f32 v[64:65], v[64:65], v[156:157]
	v_pk_mul_f32 v[66:67], v[66:67], v[158:159]
	global_store_dwordx4 v177, v[68:71], s[38:39] offset:512
	global_store_dwordx4 v177, v[64:67], s[38:39] offset:528
	s_waitcnt lgkmcnt(1)
	s_add_u32 s38, s86, 0x80000
	s_addc_u32 s39, s87, 0
	v_pk_mul_f32 v[60:61], v[60:61], v[196:197] op_sel:[0,0] op_sel_hi:[1,0]
	v_pk_mul_f32 v[62:63], v[62:63], v[196:197] op_sel:[0,0] op_sel_hi:[1,0]
	v_pk_mul_f32 v[56:57], v[56:57], v[196:197] op_sel:[0,0] op_sel_hi:[1,0]
	v_pk_mul_f32 v[58:59], v[58:59], v[196:197] op_sel:[0,0] op_sel_hi:[1,0]
	v_pk_mul_f32 v[60:61], v[60:61], v[144:145]
	v_pk_mul_f32 v[62:63], v[62:63], v[146:147]
	v_pk_mul_f32 v[56:57], v[56:57], v[148:149]
	v_pk_mul_f32 v[58:59], v[58:59], v[150:151]
	global_store_dwordx4 v177, v[60:63], s[38:39]
	global_store_dwordx4 v177, v[56:59], s[38:39] offset:16
	v_pk_mul_f32 v[52:53], v[52:53], v[196:197] op_sel:[0,0] op_sel_hi:[1,0]
	v_pk_mul_f32 v[54:55], v[54:55], v[196:197] op_sel:[0,0] op_sel_hi:[1,0]
	v_pk_mul_f32 v[48:49], v[48:49], v[196:197] op_sel:[0,0] op_sel_hi:[1,0]
	v_pk_mul_f32 v[50:51], v[50:51], v[196:197] op_sel:[0,0] op_sel_hi:[1,0]
	v_pk_mul_f32 v[52:53], v[52:53], v[152:153]
	v_pk_mul_f32 v[54:55], v[54:55], v[154:155]
	v_pk_mul_f32 v[48:49], v[48:49], v[156:157]
	v_pk_mul_f32 v[50:51], v[50:51], v[158:159]
	global_store_dwordx4 v177, v[52:55], s[38:39] offset:512
	global_store_dwordx4 v177, v[48:51], s[38:39] offset:528
	s_add_u32 s38, s86, 0x90000
	s_addc_u32 s39, s87, 0
	v_pk_mul_f32 v[44:45], v[44:45], v[196:197] op_sel:[0,1] op_sel_hi:[1,1]
	v_pk_mul_f32 v[46:47], v[46:47], v[196:197] op_sel:[0,1] op_sel_hi:[1,1]
	v_pk_mul_f32 v[40:41], v[40:41], v[196:197] op_sel:[0,1] op_sel_hi:[1,1]
	v_pk_mul_f32 v[42:43], v[42:43], v[196:197] op_sel:[0,1] op_sel_hi:[1,1]
	v_pk_mul_f32 v[44:45], v[44:45], v[144:145]
	v_pk_mul_f32 v[46:47], v[46:47], v[146:147]
	v_pk_mul_f32 v[40:41], v[40:41], v[148:149]
	v_pk_mul_f32 v[42:43], v[42:43], v[150:151]
	global_store_dwordx4 v177, v[44:47], s[38:39]
	global_store_dwordx4 v177, v[40:43], s[38:39] offset:16
	v_pk_mul_f32 v[36:37], v[36:37], v[196:197] op_sel:[0,1] op_sel_hi:[1,1]
	v_pk_mul_f32 v[38:39], v[38:39], v[196:197] op_sel:[0,1] op_sel_hi:[1,1]
	v_pk_mul_f32 v[32:33], v[32:33], v[196:197] op_sel:[0,1] op_sel_hi:[1,1]
	v_pk_mul_f32 v[34:35], v[34:35], v[196:197] op_sel:[0,1] op_sel_hi:[1,1]
	v_pk_mul_f32 v[36:37], v[36:37], v[152:153]
	v_pk_mul_f32 v[38:39], v[38:39], v[154:155]
	v_pk_mul_f32 v[32:33], v[32:33], v[156:157]
	v_pk_mul_f32 v[34:35], v[34:35], v[158:159]
	global_store_dwordx4 v177, v[36:39], s[38:39] offset:512
	global_store_dwordx4 v177, v[32:35], s[38:39] offset:528
	s_waitcnt lgkmcnt(0)
	s_add_u32 s38, s86, 0xa0000
	s_addc_u32 s39, s87, 0
	v_pk_mul_f32 v[28:29], v[28:29], v[198:199] op_sel:[0,0] op_sel_hi:[1,0]
	v_pk_mul_f32 v[30:31], v[30:31], v[198:199] op_sel:[0,0] op_sel_hi:[1,0]
	v_pk_mul_f32 v[24:25], v[24:25], v[198:199] op_sel:[0,0] op_sel_hi:[1,0]
	v_pk_mul_f32 v[26:27], v[26:27], v[198:199] op_sel:[0,0] op_sel_hi:[1,0]
	v_pk_mul_f32 v[28:29], v[28:29], v[144:145]
	v_pk_mul_f32 v[30:31], v[30:31], v[146:147]
	v_pk_mul_f32 v[24:25], v[24:25], v[148:149]
	v_pk_mul_f32 v[26:27], v[26:27], v[150:151]
	global_store_dwordx4 v177, v[28:31], s[38:39]
	global_store_dwordx4 v177, v[24:27], s[38:39] offset:16
	v_pk_mul_f32 v[20:21], v[20:21], v[198:199] op_sel:[0,0] op_sel_hi:[1,0]
	v_pk_mul_f32 v[22:23], v[22:23], v[198:199] op_sel:[0,0] op_sel_hi:[1,0]
	v_pk_mul_f32 v[16:17], v[16:17], v[198:199] op_sel:[0,0] op_sel_hi:[1,0]
	v_pk_mul_f32 v[18:19], v[18:19], v[198:199] op_sel:[0,0] op_sel_hi:[1,0]
	v_pk_mul_f32 v[20:21], v[20:21], v[152:153]
	v_pk_mul_f32 v[22:23], v[22:23], v[154:155]
	v_pk_mul_f32 v[16:17], v[16:17], v[156:157]
	v_pk_mul_f32 v[18:19], v[18:19], v[158:159]
	global_store_dwordx4 v177, v[20:23], s[38:39] offset:512
	global_store_dwordx4 v177, v[16:19], s[38:39] offset:528
	s_add_u32 s38, s86, 0xb0000
	s_addc_u32 s39, s87, 0
	v_pk_mul_f32 v[172:173], v[172:173], v[198:199] op_sel:[0,1] op_sel_hi:[1,1]
	v_pk_mul_f32 v[174:175], v[174:175], v[198:199] op_sel:[0,1] op_sel_hi:[1,1]
	v_pk_mul_f32 v[168:169], v[168:169], v[198:199] op_sel:[0,1] op_sel_hi:[1,1]
	v_pk_mul_f32 v[170:171], v[170:171], v[198:199] op_sel:[0,1] op_sel_hi:[1,1]
	v_pk_mul_f32 v[172:173], v[172:173], v[144:145]
	v_pk_mul_f32 v[174:175], v[174:175], v[146:147]
	v_pk_mul_f32 v[168:169], v[168:169], v[148:149]
	v_pk_mul_f32 v[170:171], v[170:171], v[150:151]
	global_store_dwordx4 v177, v[172:175], s[38:39]
	global_store_dwordx4 v177, v[168:171], s[38:39] offset:16
	v_pk_mul_f32 v[164:165], v[164:165], v[198:199] op_sel:[0,1] op_sel_hi:[1,1]
	v_pk_mul_f32 v[166:167], v[166:167], v[198:199] op_sel:[0,1] op_sel_hi:[1,1]
	v_pk_mul_f32 v[160:161], v[160:161], v[198:199] op_sel:[0,1] op_sel_hi:[1,1]
	v_pk_mul_f32 v[162:163], v[162:163], v[198:199] op_sel:[0,1] op_sel_hi:[1,1]
	v_pk_mul_f32 v[164:165], v[164:165], v[152:153]
	v_pk_mul_f32 v[166:167], v[166:167], v[154:155]
	v_pk_mul_f32 v[160:161], v[160:161], v[156:157]
	v_pk_mul_f32 v[162:163], v[162:163], v[158:159]
	global_store_dwordx4 v177, v[164:167], s[38:39] offset:512
	global_store_dwordx4 v177, v[160:163], s[38:39] offset:528
	s_andn2_b64 vcc, exec, s[6:7]
	s_mov_b64 s[6:7], -1
	s_waitcnt lgkmcnt(0)
	s_cbranch_vccnz .LBB0_782
	s_andn2_b64 vcc, exec, s[16:17]
	s_cbranch_vccnz .LBB0_781
	s_barrier
	s_branch .LBB0_781
